# dn_pre forward substitution kept in registers: operands loaded up front, C-layout to B-operand transposition by permlane16/32 swaps instead of LDS round trips
# speedup vs baseline: 1.0054x; 1.0022x over previous
.LBB0_419:
	s_or_b64 exec, exec, s[36:37]
	s_lshl_b32 s2, s41, 7
	v_lshlrev_b32_e32 v13, 2, v3
	v_or_b32_e32 v12, s2, v13
	v_mul_u32_u24_e32 v4, 0x840, v1
	v_add_u32_e32 v160, v12, v4
	v_mul_u32_u24_e32 v4, 0x110, v1
	s_mov_b32 s2, 0x8400
	v_add3_u32 v161, v4, v13, s2
	v_lshl_or_b32 v162, v1, 6, v13
	s_waitcnt lgkmcnt(0)
	s_barrier
	ds_read_b32 v80, v160 offset:0
	ds_read_b32 v81, v160 offset:528
	ds_read_b32 v82, v160 offset:1056
	ds_read_b32 v83, v160 offset:1584
	ds_read_b32 v84, v160 offset:64
	ds_read_b32 v85, v160 offset:592
	ds_read_b32 v86, v160 offset:1120
	ds_read_b32 v87, v160 offset:1648
	ds_read_b32 v88, v160 offset:8448
	ds_read_b32 v89, v160 offset:8976
	ds_read_b32 v90, v160 offset:9504
	ds_read_b32 v91, v160 offset:10032
	ds_read_b32 v92, v160 offset:8512
	ds_read_b32 v93, v160 offset:9040
	ds_read_b32 v94, v160 offset:9568
	ds_read_b32 v95, v160 offset:10096
	ds_read_b32 v96, v160 offset:16896
	ds_read_b32 v97, v160 offset:17424
	ds_read_b32 v98, v160 offset:17952
	ds_read_b32 v99, v160 offset:18480
	ds_read_b32 v100, v160 offset:16960
	ds_read_b32 v101, v160 offset:17488
	ds_read_b32 v102, v160 offset:18016
	ds_read_b32 v103, v160 offset:18544
	ds_read_b32 v104, v160 offset:25344
	ds_read_b32 v105, v160 offset:25872
	ds_read_b32 v106, v160 offset:26400
	ds_read_b32 v107, v160 offset:26928
	ds_read_b32 v108, v160 offset:25408
	ds_read_b32 v109, v160 offset:25936
	ds_read_b32 v110, v160 offset:26464
	ds_read_b32 v111, v160 offset:26992
	ds_read_b32 v136, v162 offset:51200
	ds_read_b32 v137, v162 offset:51456
	ds_read_b32 v138, v162 offset:51712
	ds_read_b32 v139, v162 offset:51968
	ds_read_b32 v140, v162 offset:52224
	ds_read_b32 v141, v162 offset:52480
	ds_read_b32 v142, v162 offset:52736
	ds_read_b32 v143, v162 offset:52992
	ds_read_b32 v144, v162 offset:53248
	ds_read_b32 v145, v162 offset:53504
	ds_read_b32 v146, v162 offset:53760
	ds_read_b32 v147, v162 offset:54016
	ds_read_b32 v148, v162 offset:54272
	ds_read_b32 v149, v162 offset:54528
	ds_read_b32 v150, v162 offset:54784
	ds_read_b32 v151, v162 offset:55040
	ds_read_b32 v112, v161 offset:64
	ds_read_b32 v113, v161 offset:1152
	ds_read_b32 v114, v161 offset:2240
	ds_read_b32 v115, v161 offset:3328
	ds_read_b32 v116, v161 offset:128
	ds_read_b32 v117, v161 offset:1216
	ds_read_b32 v118, v161 offset:2304
	ds_read_b32 v119, v161 offset:3392
	ds_read_b32 v120, v161 offset:4480
	ds_read_b32 v121, v161 offset:5568
	ds_read_b32 v122, v161 offset:6656
	ds_read_b32 v123, v161 offset:7744
	ds_read_b32 v124, v161 offset:192
	ds_read_b32 v125, v161 offset:1280
	ds_read_b32 v126, v161 offset:2368
	ds_read_b32 v127, v161 offset:3456
	ds_read_b32 v128, v161 offset:4544
	ds_read_b32 v129, v161 offset:5632
	ds_read_b32 v130, v161 offset:6720
	ds_read_b32 v131, v161 offset:7808
	ds_read_b32 v132, v161 offset:8896
	ds_read_b32 v133, v161 offset:9984
	ds_read_b32 v134, v161 offset:11072
	ds_read_b32 v135, v161 offset:12160
	s_waitcnt lgkmcnt(0)
	v_xor_b32_e32 v112, 0x80000000, v112
	v_xor_b32_e32 v113, 0x80000000, v113
	v_xor_b32_e32 v114, 0x80000000, v114
	v_xor_b32_e32 v115, 0x80000000, v115
	v_xor_b32_e32 v116, 0x80000000, v116
	v_xor_b32_e32 v117, 0x80000000, v117
	v_xor_b32_e32 v118, 0x80000000, v118
	v_xor_b32_e32 v119, 0x80000000, v119
	v_xor_b32_e32 v120, 0x80000000, v120
	v_xor_b32_e32 v121, 0x80000000, v121
	v_xor_b32_e32 v122, 0x80000000, v122
	v_xor_b32_e32 v123, 0x80000000, v123
	v_xor_b32_e32 v124, 0x80000000, v124
	v_xor_b32_e32 v125, 0x80000000, v125
	v_xor_b32_e32 v126, 0x80000000, v126
	v_xor_b32_e32 v127, 0x80000000, v127
	v_xor_b32_e32 v128, 0x80000000, v128
	v_xor_b32_e32 v129, 0x80000000, v129
	v_xor_b32_e32 v130, 0x80000000, v130
	v_xor_b32_e32 v131, 0x80000000, v131
	v_xor_b32_e32 v132, 0x80000000, v132
	v_xor_b32_e32 v133, 0x80000000, v133
	v_xor_b32_e32 v134, 0x80000000, v134
	v_xor_b32_e32 v135, 0x80000000, v135
	s_nop 11
	v_permlane16_swap_b32_e32 v80, v81
	v_permlane16_swap_b32_e32 v82, v83
	s_nop 1
	v_permlane32_swap_b32_e32 v80, v82
	v_permlane32_swap_b32_e32 v81, v83
	v_permlane16_swap_b32_e32 v84, v85
	v_permlane16_swap_b32_e32 v86, v87
	s_nop 1
	v_permlane32_swap_b32_e32 v84, v86
	v_permlane32_swap_b32_e32 v85, v87
	s_nop 3
	v_mfma_f32_16x16x4_f32 v[152:155], v136, v80, 0
	v_mfma_f32_16x16x4_f32 v[156:159], v136, v84, 0
	v_mfma_f32_16x16x4_f32 v[152:155], v137, v81, v[152:155]
	v_mfma_f32_16x16x4_f32 v[156:159], v137, v85, v[156:159]
	v_mfma_f32_16x16x4_f32 v[152:155], v138, v82, v[152:155]
	v_mfma_f32_16x16x4_f32 v[156:159], v138, v86, v[156:159]
	v_mfma_f32_16x16x4_f32 v[152:155], v139, v83, v[152:155]
	v_mfma_f32_16x16x4_f32 v[156:159], v139, v87, v[156:159]
	s_nop 11
	ds_write_b32 v160, v152 offset:0
	ds_write_b32 v160, v153 offset:528
	ds_write_b32 v160, v154 offset:1056
	ds_write_b32 v160, v155 offset:1584
	ds_write_b32 v160, v156 offset:64
	ds_write_b32 v160, v157 offset:592
	ds_write_b32 v160, v158 offset:1120
	ds_write_b32 v160, v159 offset:1648
	s_nop 1
	v_permlane16_swap_b32_e32 v152, v153
	v_permlane16_swap_b32_e32 v154, v155
	s_nop 1
	v_permlane32_swap_b32_e32 v152, v154
	v_permlane32_swap_b32_e32 v153, v155
	v_permlane16_swap_b32_e32 v156, v157
	v_permlane16_swap_b32_e32 v158, v159
	s_nop 1
	v_permlane32_swap_b32_e32 v156, v158
	v_permlane32_swap_b32_e32 v157, v159
	s_nop 3
	v_mfma_f32_16x16x4_f32 v[88:91], v112, v152, v[88:91]
	v_mfma_f32_16x16x4_f32 v[92:95], v112, v156, v[92:95]
	v_mfma_f32_16x16x4_f32 v[88:91], v113, v153, v[88:91]
	v_mfma_f32_16x16x4_f32 v[92:95], v113, v157, v[92:95]
	v_mfma_f32_16x16x4_f32 v[88:91], v114, v154, v[88:91]
	v_mfma_f32_16x16x4_f32 v[92:95], v114, v158, v[92:95]
	v_mfma_f32_16x16x4_f32 v[88:91], v115, v155, v[88:91]
	v_mfma_f32_16x16x4_f32 v[92:95], v115, v159, v[92:95]
	v_mfma_f32_16x16x4_f32 v[96:99], v116, v152, v[96:99]
	v_mfma_f32_16x16x4_f32 v[100:103], v116, v156, v[100:103]
	v_mfma_f32_16x16x4_f32 v[96:99], v117, v153, v[96:99]
	v_mfma_f32_16x16x4_f32 v[100:103], v117, v157, v[100:103]
	v_mfma_f32_16x16x4_f32 v[96:99], v118, v154, v[96:99]
	v_mfma_f32_16x16x4_f32 v[100:103], v118, v158, v[100:103]
	v_mfma_f32_16x16x4_f32 v[96:99], v119, v155, v[96:99]
	v_mfma_f32_16x16x4_f32 v[100:103], v119, v159, v[100:103]
	v_mfma_f32_16x16x4_f32 v[104:107], v124, v152, v[104:107]
	v_mfma_f32_16x16x4_f32 v[108:111], v124, v156, v[108:111]
	v_mfma_f32_16x16x4_f32 v[104:107], v125, v153, v[104:107]
	v_mfma_f32_16x16x4_f32 v[108:111], v125, v157, v[108:111]
	v_mfma_f32_16x16x4_f32 v[104:107], v126, v154, v[104:107]
	v_mfma_f32_16x16x4_f32 v[108:111], v126, v158, v[108:111]
	v_mfma_f32_16x16x4_f32 v[104:107], v127, v155, v[104:107]
	v_mfma_f32_16x16x4_f32 v[108:111], v127, v159, v[108:111]
	s_nop 11
	v_permlane16_swap_b32_e32 v88, v89
	v_permlane16_swap_b32_e32 v90, v91
	s_nop 1
	v_permlane32_swap_b32_e32 v88, v90
	v_permlane32_swap_b32_e32 v89, v91
	v_permlane16_swap_b32_e32 v92, v93
	v_permlane16_swap_b32_e32 v94, v95
	s_nop 1
	v_permlane32_swap_b32_e32 v92, v94
	v_permlane32_swap_b32_e32 v93, v95
	s_nop 3
	v_mfma_f32_16x16x4_f32 v[152:155], v140, v88, 0
	v_mfma_f32_16x16x4_f32 v[156:159], v140, v92, 0
	v_mfma_f32_16x16x4_f32 v[152:155], v141, v89, v[152:155]
	v_mfma_f32_16x16x4_f32 v[156:159], v141, v93, v[156:159]
	v_mfma_f32_16x16x4_f32 v[152:155], v142, v90, v[152:155]
	v_mfma_f32_16x16x4_f32 v[156:159], v142, v94, v[156:159]
	v_mfma_f32_16x16x4_f32 v[152:155], v143, v91, v[152:155]
	v_mfma_f32_16x16x4_f32 v[156:159], v143, v95, v[156:159]
	s_nop 11
	ds_write_b32 v160, v152 offset:8448
	ds_write_b32 v160, v153 offset:8976
	ds_write_b32 v160, v154 offset:9504
	ds_write_b32 v160, v155 offset:10032
	ds_write_b32 v160, v156 offset:8512
	ds_write_b32 v160, v157 offset:9040
	ds_write_b32 v160, v158 offset:9568
	ds_write_b32 v160, v159 offset:10096
	s_nop 1
	v_permlane16_swap_b32_e32 v152, v153
	v_permlane16_swap_b32_e32 v154, v155
	s_nop 1
	v_permlane32_swap_b32_e32 v152, v154
	v_permlane32_swap_b32_e32 v153, v155
	v_permlane16_swap_b32_e32 v156, v157
	v_permlane16_swap_b32_e32 v158, v159
	s_nop 1
	v_permlane32_swap_b32_e32 v156, v158
	v_permlane32_swap_b32_e32 v157, v159
	s_nop 3
	v_mfma_f32_16x16x4_f32 v[96:99], v120, v152, v[96:99]
	v_mfma_f32_16x16x4_f32 v[100:103], v120, v156, v[100:103]
	v_mfma_f32_16x16x4_f32 v[96:99], v121, v153, v[96:99]
	v_mfma_f32_16x16x4_f32 v[100:103], v121, v157, v[100:103]
	v_mfma_f32_16x16x4_f32 v[96:99], v122, v154, v[96:99]
	v_mfma_f32_16x16x4_f32 v[100:103], v122, v158, v[100:103]
	v_mfma_f32_16x16x4_f32 v[96:99], v123, v155, v[96:99]
	v_mfma_f32_16x16x4_f32 v[100:103], v123, v159, v[100:103]
	v_mfma_f32_16x16x4_f32 v[104:107], v128, v152, v[104:107]
	v_mfma_f32_16x16x4_f32 v[108:111], v128, v156, v[108:111]
	v_mfma_f32_16x16x4_f32 v[104:107], v129, v153, v[104:107]
	v_mfma_f32_16x16x4_f32 v[108:111], v129, v157, v[108:111]
	v_mfma_f32_16x16x4_f32 v[104:107], v130, v154, v[104:107]
	v_mfma_f32_16x16x4_f32 v[108:111], v130, v158, v[108:111]
	v_mfma_f32_16x16x4_f32 v[104:107], v131, v155, v[104:107]
	v_mfma_f32_16x16x4_f32 v[108:111], v131, v159, v[108:111]
	s_nop 11
	v_permlane16_swap_b32_e32 v96, v97
	v_permlane16_swap_b32_e32 v98, v99
	s_nop 1
	v_permlane32_swap_b32_e32 v96, v98
	v_permlane32_swap_b32_e32 v97, v99
	v_permlane16_swap_b32_e32 v100, v101
	v_permlane16_swap_b32_e32 v102, v103
	s_nop 1
	v_permlane32_swap_b32_e32 v100, v102
	v_permlane32_swap_b32_e32 v101, v103
	s_nop 3
	v_mfma_f32_16x16x4_f32 v[152:155], v144, v96, 0
	v_mfma_f32_16x16x4_f32 v[156:159], v144, v100, 0
	v_mfma_f32_16x16x4_f32 v[152:155], v145, v97, v[152:155]
	v_mfma_f32_16x16x4_f32 v[156:159], v145, v101, v[156:159]
	v_mfma_f32_16x16x4_f32 v[152:155], v146, v98, v[152:155]
	v_mfma_f32_16x16x4_f32 v[156:159], v146, v102, v[156:159]
	v_mfma_f32_16x16x4_f32 v[152:155], v147, v99, v[152:155]
	v_mfma_f32_16x16x4_f32 v[156:159], v147, v103, v[156:159]
	s_nop 11
	ds_write_b32 v160, v152 offset:16896
	ds_write_b32 v160, v153 offset:17424
	ds_write_b32 v160, v154 offset:17952
	ds_write_b32 v160, v155 offset:18480
	ds_write_b32 v160, v156 offset:16960
	ds_write_b32 v160, v157 offset:17488
	ds_write_b32 v160, v158 offset:18016
	ds_write_b32 v160, v159 offset:18544
	s_nop 1
	v_permlane16_swap_b32_e32 v152, v153
	v_permlane16_swap_b32_e32 v154, v155
	s_nop 1
	v_permlane32_swap_b32_e32 v152, v154
	v_permlane32_swap_b32_e32 v153, v155
	v_permlane16_swap_b32_e32 v156, v157
	v_permlane16_swap_b32_e32 v158, v159
	s_nop 1
	v_permlane32_swap_b32_e32 v156, v158
	v_permlane32_swap_b32_e32 v157, v159
	s_nop 3
	v_mfma_f32_16x16x4_f32 v[104:107], v132, v152, v[104:107]
	v_mfma_f32_16x16x4_f32 v[108:111], v132, v156, v[108:111]
	v_mfma_f32_16x16x4_f32 v[104:107], v133, v153, v[104:107]
	v_mfma_f32_16x16x4_f32 v[108:111], v133, v157, v[108:111]
	v_mfma_f32_16x16x4_f32 v[104:107], v134, v154, v[104:107]
	v_mfma_f32_16x16x4_f32 v[108:111], v134, v158, v[108:111]
	v_mfma_f32_16x16x4_f32 v[104:107], v135, v155, v[104:107]
	v_mfma_f32_16x16x4_f32 v[108:111], v135, v159, v[108:111]
	s_nop 11
	v_permlane16_swap_b32_e32 v104, v105
	v_permlane16_swap_b32_e32 v106, v107
	s_nop 1
	v_permlane32_swap_b32_e32 v104, v106
	v_permlane32_swap_b32_e32 v105, v107
	v_permlane16_swap_b32_e32 v108, v109
	v_permlane16_swap_b32_e32 v110, v111
	s_nop 1
	v_permlane32_swap_b32_e32 v108, v110
	v_permlane32_swap_b32_e32 v109, v111
	s_nop 3
	v_mfma_f32_16x16x4_f32 v[152:155], v148, v104, 0
	v_mfma_f32_16x16x4_f32 v[156:159], v148, v108, 0
	v_mfma_f32_16x16x4_f32 v[152:155], v149, v105, v[152:155]
	v_mfma_f32_16x16x4_f32 v[156:159], v149, v109, v[156:159]
	v_mfma_f32_16x16x4_f32 v[152:155], v150, v106, v[152:155]
	v_mfma_f32_16x16x4_f32 v[156:159], v150, v110, v[156:159]
	v_mfma_f32_16x16x4_f32 v[152:155], v151, v107, v[152:155]
	v_mfma_f32_16x16x4_f32 v[156:159], v151, v111, v[156:159]
	s_nop 11
	ds_write_b32 v160, v152 offset:25344
	ds_write_b32 v160, v153 offset:25872
	ds_write_b32 v160, v154 offset:26400
	ds_write_b32 v160, v155 offset:26928
	ds_write_b32 v160, v156 offset:25408
	ds_write_b32 v160, v157 offset:25936
	ds_write_b32 v160, v158 offset:26464
	ds_write_b32 v160, v159 offset:26992
	s_branch .LBB0_396
